# v84 + 7.12 ballot trim in the 6 GEMM tile headers (v_cndmask+v_cmp_ne re-deriving exec&~mask -> one s_andn2_b64) + LDS-offset constant folding in the GN K-loop
# speedup vs baseline: 1.0006x; 1.0006x over previous
; template <class Epi, bool ALIGN_EPI = PG8_ALIGN, bool SP2 = PG8_SP2>
; __device__ __forceinline__ void gemm_phase(LAS uchar* lds, const Gemm g, const StaticOrder& S, const Epi& E) {
;     ...
;         const bool has_next = S.next(ui + 1, nxt);
;         const char* nA = has_next ? (const char*)g.A + (size_t)nxt.pm * tstepA : cA; const char* nB = has_next ? (const char*)g.Bt + (size_t)nxt.pn * tstepB : cB;
.LBB0_340:
	s_andn2_b64 s[0:1], exec, s[6:7]
	s_andn2_b64 vcc, exec, s[6:7]
	s_mov_b64 s[6:7], s[16:17]
	s_cbranch_vccnz .LBB0_342
	v_readlane_b32 s40, v254, 0
	s_mul_i32 s6, s35, 0x88000
	v_readlane_b32 s44, v254, 4
	s_mul_hi_i32 s7, s35, 0x88000
	v_readlane_b32 s45, v254, 5
	s_add_u32 s6, s44, s6
	s_addc_u32 s7, s45, s7
	v_readlane_b32 s41, v254, 1
	v_readlane_b32 s42, v254, 2
	v_readlane_b32 s43, v254, 3
	v_readlane_b32 s46, v254, 6
	v_readlane_b32 s47, v254, 7

; template <class Epi, bool ALIGN_EPI = PG8_ALIGN, bool SP2 = PG8_SP2>
; __device__ __forceinline__ void gemm_phase(LAS uchar* lds, const Gemm g, const StaticOrder& S, const Epi& E) {
;     ...
;         const bool has_next = S.next(ui + 1, nxt);
;         const char* nA = has_next ? (const char*)g.A + (size_t)nxt.pm * tstepA : cA; const char* nB = has_next ? (const char*)g.Bt + (size_t)nxt.pn * tstepB : cB;
.LBB0_573:
	s_nop 0
	s_andn2_b64 s[6:7], exec, s[0:1]
	s_andn2_b64 vcc, exec, s[0:1]
	s_mov_b64 s[0:1], s[14:15]
	s_cbranch_vccnz .LBB0_575
	s_mul_i32 s0, s35, 0x308000
	s_mul_hi_i32 s1, s35, 0x308000
	s_add_u32 s0, s90, s0
	s_addc_u32 s1, s91, s1

; #define PG8_STAGE(bufoff, gbase, voff) do { _Pragma("unroll") for (int _i = 0; _i < 2; ++_i) \
;         __builtin_amdgcn_global_load_lds((const unsigned*)((const char*)(gbase) + (voff)[_i]), (LAS unsigned*)(lds + (bufoff) + ldsw + _i * 8192), 16, 0, 0); } while (0)
; #define PG8_LDA(dst, b, h) do { _Pragma("unroll") for (int m = 0; m < 4; ++m) _Pragma("unroll") for (int k = 0; k < 2; ++k) dst[m][k] = *(const LAS bf16x8*)(lds + PG8_SA(b, h) + aoff + m * 2048 + k * 1024); } while (0)
; #define PG8_LDB(dst, b, h) do { _Pragma("unroll") for (int n = 0; n < 2; ++n) _Pragma("unroll") for (int k = 0; k < 2; ++k) dst[n][k] = *(const LAS bf16x8*)(lds + PG8_SB(b, h) + boff + n * 2048 + k * 1024); } while (0)
; #define PG8_MMA(ai, bj, At, Bt) do { __builtin_amdgcn_s_setprio(1); _Pragma("unroll") for (int m = 0; m < 4; ++m) _Pragma("unroll") for (int n = 0; n < 2; ++n) _Pragma("unroll") for (int k = 0; k < 2; ++k) \
;         acc[ai][bj][m][n] = __builtin_amdgcn_mfma_f32_16x16x32_bf16(Bt[n][k], At[m][k], acc[ai][bj][m][n], 0, 0, 0); __builtin_amdgcn_s_setprio(0); } while (0)
; #define PG8_WAIT_V(n) asm volatile("s_waitcnt vmcnt(" #n ")" ::: "memory")
; #define PG8_WAIT_L(n) asm volatile("s_waitcnt lgkmcnt(" #n ")" ::: "memory")
; #define PG8_BAR __builtin_amdgcn_s_barrier()
; #define PG8_SCHED __builtin_amdgcn_sched_barrier(0)
; template <class Epi, bool ALIGN_EPI = PG8_ALIGN, bool SP2 = PG8_SP2>
; __device__ __forceinline__ void gemm_phase(LAS uchar* lds, const Gemm g, const StaticOrder& S, const Epi& E) {
;     ...
;             const bool last = (t == nt - 2);
;             const char* a1 = cA + (size_t)(t + 1) * kstep;
;             const char* a2 = last ? nA : cA + (size_t)(t + 2) * kstep; const char* b2 = last ? nB : cB + (size_t)(t + 2) * kstep;
;             const char* a3 = a2 + kstep; const char* b3 = b2 + kstep;
;             if constexpr (SP2) {
;             PG8_LDB(B0, 0, 0); PG8_LDB(B1, 0, 1); PG8_SCHED; PG8_LDA(At, 0, 0); PG8_STAGE(PG8_SA(1, 1), a1 + hstepA, voffA);
;             PG8_WAIT_V(8); PG8_WAIT_L(0); PG8_BAR; PG8_MMA(0, 0, At, B0); PG8_MMA(0, 1, At, B1); PG8_BAR; PG8_SCHED;
;             PG8_LDA(At, 0, 1); PG8_STAGE(PG8_SB(0, 0), b2, voffB); PG8_STAGE(PG8_SB(0, 1), b2 + hstepB, voffB); PG8_STAGE(PG8_SA(0, 0), a2, voffA);
.LBB0_580:
	s_add_i32 s42, s42, 2
	s_add_u32 s4, s14, s18
	s_addc_u32 s5, s15, s19
	s_add_u32 s4, s4, 0x100
	s_addc_u32 s5, s5, 0
	s_add_u32 s43, s38, s18
	s_addc_u32 s44, s39, s19
	s_cmpk_eq_i32 s18, 0xf00
	s_cselect_b32 s21, s1, s5
	s_cselect_b32 s20, s0, s4
	v_add_u32_e32 v1, 0x10000, v168
	s_cselect_b32 s5, s13, s44
	s_cselect_b32 s4, s12, s43
	ds_read_b128 v[174:177], v1
	ds_read_b128 v[178:181], v1 offset:1024
	ds_read_b128 v[184:187], v1 offset:2048
	ds_read_b128 v[188:191], v1 offset:3072
	v_add_u32_e32 v1, 0x14000, v168
	ds_read_b128 v[192:195], v1
	ds_read_b128 v[196:199], v1 offset:1024
	ds_read_b128 v[200:203], v1 offset:2048
	ds_read_b128 v[204:207], v1 offset:3072
	v_lshl_add_u64 v[2:3], v[164:165], 0, s[18:19]
	s_add_i32 m0, s25, 0xc000
	ds_read_b128 v[208:211], v170
	ds_read_b128 v[212:215], v170 offset:1024
	ds_read_b128 v[216:219], v170 offset:2048
	ds_read_b128 v[220:223], v170 offset:3072
	ds_read_b128 v[224:227], v170 offset:4096
	ds_read_b128 v[228:231], v170 offset:5120
	ds_read_b128 v[232:235], v170 offset:6144
	ds_read_b128 v[236:239], v170 offset:7168
	global_load_lds_dwordx4 v[2:3], off
	s_add_i32 m0, s25, 0xe000
	v_lshl_add_u64 v[2:3], v[166:167], 0, s[18:19]
	global_load_lds_dwordx4 v[2:3], off
	s_waitcnt vmcnt(8)
	s_waitcnt lgkmcnt(0)
	s_setprio 1
	s_barrier
	v_mfma_f32_16x16x32_bf16 v[128:131], v[174:177], v[208:211], v[128:131]
	v_mfma_f32_16x16x32_bf16 v[124:127], v[184:187], v[208:211], v[124:127]
	v_mfma_f32_16x16x32_bf16 v[112:115], v[174:177], v[216:219], v[112:115]
	v_mfma_f32_16x16x32_bf16 v[108:111], v[184:187], v[216:219], v[108:111]
	v_mfma_f32_16x16x32_bf16 v[96:99], v[174:177], v[224:227], v[96:99]
	v_mfma_f32_16x16x32_bf16 v[92:95], v[184:187], v[224:227], v[92:95]
	v_mfma_f32_16x16x32_bf16 v[80:83], v[174:177], v[232:235], v[80:83]
	v_mfma_f32_16x16x32_bf16 v[76:79], v[184:187], v[232:235], v[76:79]
	v_mfma_f32_16x16x32_bf16 v[128:131], v[178:181], v[212:215], v[128:131]
	v_mfma_f32_16x16x32_bf16 v[124:127], v[188:191], v[212:215], v[124:127]
	v_mfma_f32_16x16x32_bf16 v[112:115], v[178:181], v[220:223], v[112:115]
	v_mfma_f32_16x16x32_bf16 v[108:111], v[188:191], v[220:223], v[108:111]
	v_mfma_f32_16x16x32_bf16 v[96:99], v[178:181], v[228:231], v[96:99]
	v_mfma_f32_16x16x32_bf16 v[92:95], v[188:191], v[228:231], v[92:95]
	v_mfma_f32_16x16x32_bf16 v[80:83], v[178:181], v[236:239], v[80:83]
	v_mfma_f32_16x16x32_bf16 v[76:79], v[188:191], v[236:239], v[76:79]
	v_mfma_f32_16x16x32_bf16 v[120:123], v[192:195], v[208:211], v[120:123]
	v_mfma_f32_16x16x32_bf16 v[116:119], v[200:203], v[208:211], v[116:119]
	v_mfma_f32_16x16x32_bf16 v[104:107], v[192:195], v[216:219], v[104:107]
	v_mfma_f32_16x16x32_bf16 v[100:103], v[200:203], v[216:219], v[100:103]
	v_mfma_f32_16x16x32_bf16 v[88:91], v[192:195], v[224:227], v[88:91]
	v_mfma_f32_16x16x32_bf16 v[84:87], v[200:203], v[224:227], v[84:87]
	v_mfma_f32_16x16x32_bf16 v[72:75], v[192:195], v[232:235], v[72:75]
	v_mfma_f32_16x16x32_bf16 v[68:71], v[200:203], v[232:235], v[68:71]
	v_mfma_f32_16x16x32_bf16 v[120:123], v[196:199], v[212:215], v[120:123]
	v_mfma_f32_16x16x32_bf16 v[116:119], v[204:207], v[212:215], v[116:119]
	v_mfma_f32_16x16x32_bf16 v[104:107], v[196:199], v[220:223], v[104:107]
	v_mfma_f32_16x16x32_bf16 v[100:103], v[204:207], v[220:223], v[100:103]
	v_mfma_f32_16x16x32_bf16 v[88:91], v[196:199], v[228:231], v[88:91]
	v_mfma_f32_16x16x32_bf16 v[84:87], v[204:207], v[228:231], v[84:87]
	v_mfma_f32_16x16x32_bf16 v[72:75], v[196:199], v[236:239], v[72:75]
	v_mfma_f32_16x16x32_bf16 v[68:71], v[204:207], v[236:239], v[68:71]
	s_barrier
	s_setprio 0
	v_lshl_add_u64 v[240:241], s[4:5], 0, v[134:135]
	s_add_i32 m0, s24, 0x10000
	ds_read_b128 v[208:211], v170 offset:16384
	ds_read_b128 v[212:215], v170 offset:17408
	ds_read_b128 v[216:219], v170 offset:18432
	ds_read_b128 v[220:223], v170 offset:19456
	ds_read_b128 v[224:227], v170 offset:20480
	ds_read_b128 v[228:231], v170 offset:21504
	ds_read_b128 v[232:235], v170 offset:22528
	ds_read_b128 v[236:239], v170 offset:23552
	global_load_lds_dwordx4 v[240:241], off
	s_add_i32 m0, s24, 0x12000
	s_add_u32 s44, s4, 0x84000
	v_lshl_add_u64 v[242:243], s[4:5], 0, v[158:159]
	s_addc_u32 s45, s5, 0
	global_load_lds_dwordx4 v[242:243], off
	s_add_i32 m0, s24, 0x14000
	v_lshl_add_u64 v[2:3], s[44:45], 0, v[134:135]
	global_load_lds_dwordx4 v[2:3], off
	s_add_i32 m0, s24, 0x16000
	v_lshl_add_u64 v[2:3], s[44:45], 0, v[158:159]
	global_load_lds_dwordx4 v[2:3], off
	s_mov_b32 m0, s25
	v_lshl_add_u64 v[244:245], s[20:21], 0, v[132:133]
	global_load_lds_dwordx4 v[244:245], off
	s_mov_b32 m0, s26
	v_lshl_add_u64 v[246:247], s[20:21], 0, v[156:157]
	global_load_lds_dwordx4 v[246:247], off
	s_waitcnt vmcnt(8)
	s_waitcnt lgkmcnt(0)
	s_setprio 1
	s_barrier
; #define PG8_STAGE(bufoff, gbase, voff) do { _Pragma("unroll") for (int _i = 0; _i < 2; ++_i) \
;         __builtin_amdgcn_global_load_lds((const unsigned*)((const char*)(gbase) + (voff)[_i]), (LAS unsigned*)(lds + (bufoff) + ldsw + _i * 8192), 16, 0, 0); } while (0)
; #define PG8_LDA(dst, b, h) do { _Pragma("unroll") for (int m = 0; m < 4; ++m) _Pragma("unroll") for (int k = 0; k < 2; ++k) dst[m][k] = *(const LAS bf16x8*)(lds + PG8_SA(b, h) + aoff + m * 2048 + k * 1024); } while (0)
; #define PG8_LDB(dst, b, h) do { _Pragma("unroll") for (int n = 0; n < 2; ++n) _Pragma("unroll") for (int k = 0; k < 2; ++k) dst[n][k] = *(const LAS bf16x8*)(lds + PG8_SB(b, h) + boff + n * 2048 + k * 1024); } while (0)
; #define PG8_MMA(ai, bj, At, Bt) do { __builtin_amdgcn_s_setprio(1); _Pragma("unroll") for (int m = 0; m < 4; ++m) _Pragma("unroll") for (int n = 0; n < 2; ++n) _Pragma("unroll") for (int k = 0; k < 2; ++k) \
;         acc[ai][bj][m][n] = __builtin_amdgcn_mfma_f32_16x16x32_bf16(Bt[n][k], At[m][k], acc[ai][bj][m][n], 0, 0, 0); __builtin_amdgcn_s_setprio(0); } while (0)
; #define PG8_WAIT_V(n) asm volatile("s_waitcnt vmcnt(" #n ")" ::: "memory")
; #define PG8_WAIT_L(n) asm volatile("s_waitcnt lgkmcnt(" #n ")" ::: "memory")
; #define PG8_BAR __builtin_amdgcn_s_barrier()
; #define PG8_SCHED __builtin_amdgcn_sched_barrier(0)
; template <class Epi, bool ALIGN_EPI = PG8_ALIGN, bool SP2 = PG8_SP2>
; __device__ __forceinline__ void gemm_phase(LAS uchar* lds, const Gemm g, const StaticOrder& S, const Epi& E) {
;     ...
;             PG8_WAIT_V(8); PG8_WAIT_L(0); PG8_BAR; PG8_MMA(1, 0, At, B0); PG8_MMA(1, 1, At, B1); PG8_BAR; PG8_SCHED;
;             PG8_LDB(B0, 1, 0); PG8_LDB(B1, 1, 1); PG8_SCHED; PG8_LDA(At, 1, 0); PG8_STAGE(PG8_SA(0, 1), a2 + hstepA, voffA);
;             PG8_WAIT_V(8); PG8_WAIT_L(0); PG8_BAR; PG8_MMA(0, 0, At, B0); PG8_MMA(0, 1, At, B1); PG8_BAR; PG8_SCHED;
	v_mfma_f32_16x16x32_bf16 v[64:67], v[174:177], v[208:211], v[64:67]
	v_mfma_f32_16x16x32_bf16 v[60:63], v[184:187], v[208:211], v[60:63]
	v_mfma_f32_16x16x32_bf16 v[48:51], v[174:177], v[216:219], v[48:51]
	v_mfma_f32_16x16x32_bf16 v[44:47], v[184:187], v[216:219], v[44:47]
	v_mfma_f32_16x16x32_bf16 v[32:35], v[174:177], v[224:227], v[32:35]
	v_mfma_f32_16x16x32_bf16 v[28:31], v[184:187], v[224:227], v[28:31]
	v_mfma_f32_16x16x32_bf16 v[16:19], v[174:177], v[232:235], v[16:19]
	v_mfma_f32_16x16x32_bf16 v[12:15], v[184:187], v[232:235], v[12:15]
	v_mfma_f32_16x16x32_bf16 v[64:67], v[178:181], v[212:215], v[64:67]
	v_mfma_f32_16x16x32_bf16 v[60:63], v[188:191], v[212:215], v[60:63]
	v_mfma_f32_16x16x32_bf16 v[48:51], v[178:181], v[220:223], v[48:51]
	v_mfma_f32_16x16x32_bf16 v[44:47], v[188:191], v[220:223], v[44:47]
	v_mfma_f32_16x16x32_bf16 v[32:35], v[178:181], v[228:231], v[32:35]
	v_mfma_f32_16x16x32_bf16 v[28:31], v[188:191], v[228:231], v[28:31]
	v_mfma_f32_16x16x32_bf16 v[16:19], v[178:181], v[236:239], v[16:19]
	v_mfma_f32_16x16x32_bf16 v[12:15], v[188:191], v[236:239], v[12:15]
	v_mfma_f32_16x16x32_bf16 v[56:59], v[192:195], v[208:211], v[56:59]
	v_mfma_f32_16x16x32_bf16 v[52:55], v[200:203], v[208:211], v[52:55]
	v_mfma_f32_16x16x32_bf16 v[40:43], v[192:195], v[216:219], v[40:43]
	v_mfma_f32_16x16x32_bf16 v[36:39], v[200:203], v[216:219], v[36:39]
	v_mfma_f32_16x16x32_bf16 v[24:27], v[192:195], v[224:227], v[24:27]
	v_mfma_f32_16x16x32_bf16 v[20:23], v[200:203], v[224:227], v[20:23]
	v_mfma_f32_16x16x32_bf16 v[8:11], v[192:195], v[232:235], v[8:11]
	v_mfma_f32_16x16x32_bf16 v[2:5], v[200:203], v[232:235], v[4:7]
	v_mfma_f32_16x16x32_bf16 v[56:59], v[196:199], v[212:215], v[56:59]
	v_mfma_f32_16x16x32_bf16 v[52:55], v[204:207], v[212:215], v[52:55]
	v_mfma_f32_16x16x32_bf16 v[40:43], v[196:199], v[220:223], v[40:43]
	v_mfma_f32_16x16x32_bf16 v[36:39], v[204:207], v[220:223], v[36:39]
	v_mfma_f32_16x16x32_bf16 v[24:27], v[196:199], v[228:231], v[24:27]
	v_mfma_f32_16x16x32_bf16 v[20:23], v[204:207], v[228:231], v[20:23]
	v_mfma_f32_16x16x32_bf16 v[8:11], v[196:199], v[236:239], v[8:11]
	v_mfma_f32_16x16x32_bf16 v[2:5], v[204:207], v[236:239], v[2:5]
	s_barrier
	s_setprio 0
	v_add_u32_e32 v1, 0x18000, v168
	ds_read_b128 v[174:177], v1
	ds_read_b128 v[178:181], v1 offset:1024
	ds_read_b128 v[184:187], v1 offset:2048
	ds_read_b128 v[188:191], v1 offset:3072
	v_add_u32_e32 v1, 0x1c000, v168
	ds_read_b128 v[192:195], v1
	ds_read_b128 v[196:199], v1 offset:1024
	ds_read_b128 v[200:203], v1 offset:2048
	ds_read_b128 v[204:207], v1 offset:3072
	s_add_u32 s20, s20, 0x184000
	s_addc_u32 s21, s21, 0
	s_mov_b32 m0, s27
	v_lshl_add_u64 v[6:7], s[20:21], 0, v[132:133]
	ds_read_b128 v[208:211], v170 offset:32768
	ds_read_b128 v[212:215], v170 offset:33792
	ds_read_b128 v[216:219], v170 offset:34816
	ds_read_b128 v[220:223], v170 offset:35840
	ds_read_b128 v[224:227], v170 offset:36864
	ds_read_b128 v[228:231], v170 offset:37888
	ds_read_b128 v[232:235], v170 offset:38912
	ds_read_b128 v[236:239], v170 offset:39936
	global_load_lds_dwordx4 v[6:7], off
	s_mov_b32 m0, s28
	v_lshl_add_u64 v[6:7], s[20:21], 0, v[156:157]
	global_load_lds_dwordx4 v[6:7], off
	s_waitcnt vmcnt(8)
	s_waitcnt lgkmcnt(0)
	s_setprio 1
	s_barrier
	v_mfma_f32_16x16x32_bf16 v[128:131], v[174:177], v[208:211], v[128:131]
	v_mfma_f32_16x16x32_bf16 v[124:127], v[184:187], v[208:211], v[124:127]
	v_mfma_f32_16x16x32_bf16 v[112:115], v[174:177], v[216:219], v[112:115]
	v_mfma_f32_16x16x32_bf16 v[108:111], v[184:187], v[216:219], v[108:111]
	v_mfma_f32_16x16x32_bf16 v[96:99], v[174:177], v[224:227], v[96:99]
	v_mfma_f32_16x16x32_bf16 v[92:95], v[184:187], v[224:227], v[92:95]
	v_mfma_f32_16x16x32_bf16 v[80:83], v[174:177], v[232:235], v[80:83]
	v_mfma_f32_16x16x32_bf16 v[76:79], v[184:187], v[232:235], v[76:79]
	v_mfma_f32_16x16x32_bf16 v[128:131], v[178:181], v[212:215], v[128:131]
	v_mfma_f32_16x16x32_bf16 v[124:127], v[188:191], v[212:215], v[124:127]
	v_mfma_f32_16x16x32_bf16 v[112:115], v[178:181], v[220:223], v[112:115]
	v_mfma_f32_16x16x32_bf16 v[108:111], v[188:191], v[220:223], v[108:111]
	v_mfma_f32_16x16x32_bf16 v[96:99], v[178:181], v[228:231], v[96:99]
	v_mfma_f32_16x16x32_bf16 v[92:95], v[188:191], v[228:231], v[92:95]
	v_mfma_f32_16x16x32_bf16 v[80:83], v[178:181], v[236:239], v[80:83]
	v_mfma_f32_16x16x32_bf16 v[76:79], v[188:191], v[236:239], v[76:79]
	v_mfma_f32_16x16x32_bf16 v[120:123], v[192:195], v[208:211], v[120:123]
	v_mfma_f32_16x16x32_bf16 v[116:119], v[200:203], v[208:211], v[116:119]
	v_mfma_f32_16x16x32_bf16 v[104:107], v[192:195], v[216:219], v[104:107]
	v_mfma_f32_16x16x32_bf16 v[100:103], v[200:203], v[216:219], v[100:103]
	v_mfma_f32_16x16x32_bf16 v[88:91], v[192:195], v[224:227], v[88:91]
	v_mfma_f32_16x16x32_bf16 v[84:87], v[200:203], v[224:227], v[84:87]
	v_mfma_f32_16x16x32_bf16 v[72:75], v[192:195], v[232:235], v[72:75]
	v_mfma_f32_16x16x32_bf16 v[68:71], v[200:203], v[232:235], v[68:71]
	v_mfma_f32_16x16x32_bf16 v[120:123], v[196:199], v[212:215], v[120:123]
	v_mfma_f32_16x16x32_bf16 v[116:119], v[204:207], v[212:215], v[116:119]
	v_mfma_f32_16x16x32_bf16 v[104:107], v[196:199], v[220:223], v[104:107]
	v_mfma_f32_16x16x32_bf16 v[100:103], v[204:207], v[220:223], v[100:103]
	v_mfma_f32_16x16x32_bf16 v[88:91], v[196:199], v[228:231], v[88:91]
	v_mfma_f32_16x16x32_bf16 v[84:87], v[204:207], v[228:231], v[84:87]
	v_mfma_f32_16x16x32_bf16 v[72:75], v[196:199], v[236:239], v[72:75]
	v_mfma_f32_16x16x32_bf16 v[68:71], v[204:207], v[236:239], v[68:71]
	s_barrier
; #define LAS __attribute__((address_space(3)))
; #define PG8_STAGE(bufoff, gbase, voff) do { _Pragma("unroll") for (int _i = 0; _i < 2; ++_i) \
;         __builtin_amdgcn_global_load_lds((const unsigned*)((const char*)(gbase) + (voff)[_i]), (LAS unsigned*)(lds + (bufoff) + ldsw + _i * 8192), 16, 0, 0); } while (0)
; #define PG8_LDA(dst, b, h) do { _Pragma("unroll") for (int m = 0; m < 4; ++m) _Pragma("unroll") for (int k = 0; k < 2; ++k) dst[m][k] = *(const LAS bf16x8*)(lds + PG8_SA(b, h) + aoff + m * 2048 + k * 1024); } while (0)
; #define PG8_MMA(ai, bj, At, Bt) do { __builtin_amdgcn_s_setprio(1); _Pragma("unroll") for (int m = 0; m < 4; ++m) _Pragma("unroll") for (int n = 0; n < 2; ++n) _Pragma("unroll") for (int k = 0; k < 2; ++k) \
;         acc[ai][bj][m][n] = __builtin_amdgcn_mfma_f32_16x16x32_bf16(Bt[n][k], At[m][k], acc[ai][bj][m][n], 0, 0, 0); __builtin_amdgcn_s_setprio(0); } while (0)
; #define PG8_WAIT_V(n) asm volatile("s_waitcnt vmcnt(" #n ")" ::: "memory")
; #define PG8_WAIT_L(n) asm volatile("s_waitcnt lgkmcnt(" #n ")" ::: "memory")
; #define PG8_BAR __builtin_amdgcn_s_barrier()
; #define PG8_SCHED __builtin_amdgcn_sched_barrier(0)
; template <class Epi, bool ALIGN_EPI = PG8_ALIGN, bool SP2 = PG8_SP2>
; __device__ __forceinline__ void gemm_phase(LAS uchar* lds, const Gemm g, const StaticOrder& S, const Epi& E) {
;     ...
;         for (int tb = 0; tb < nt; tb += tblk) {
;         if constexpr (Epi::GROUPS) { if (tb > 0) {
;             const LAS float* rt = (const LAS float*)(lds + LDS_RT) + ((ui & 1) * 256 + wr * 64 + fr) * 8 + ((tb >> 2) - 1);
; #pragma unroll
;             for (int a = 0; a < 2; ++a)
; #pragma unroll
;                 for (int m = 0; m < 4; ++m) { const float f = rt[(a * 128 + m * 16) * 8];
; #pragma unroll
;                     for (int b = 0; b < 2; ++b)
; #pragma unroll
;                         for (int n = 0; n < 2; ++n) acc[a][b][m][n] *= f; } } }
; #pragma unroll 1
;         for (int t = tb; t < tb + tblk; t += 2) {
;     ...
;             PG8_LDA(At, 1, 1); PG8_STAGE(PG8_SB(1, 0), b3, voffB); PG8_STAGE(PG8_SB(1, 1), b3 + hstepB, voffB); PG8_STAGE(PG8_SA(1, 0), a3, voffA);
;             PG8_WAIT_V(8); PG8_WAIT_L(0); PG8_BAR; PG8_MMA(1, 0, At, B0); PG8_MMA(1, 1, At, B1); PG8_BAR; PG8_SCHED;
	s_setprio 0
	v_lshl_add_u64 v[6:7], v[240:241], 0, s[84:85]
	s_add_i32 m0, s24, 0x18000
	ds_read_b128 v[208:211], v170 offset:49152
	ds_read_b128 v[212:215], v170 offset:50176
	ds_read_b128 v[216:219], v170 offset:51200
	ds_read_b128 v[220:223], v170 offset:52224
	ds_read_b128 v[224:227], v170 offset:53248
	ds_read_b128 v[228:231], v170 offset:54272
	ds_read_b128 v[232:235], v170 offset:55296
	ds_read_b128 v[236:239], v170 offset:56320
	global_load_lds_dwordx4 v[6:7], off
	s_add_i32 m0, s24, 0x1a000
	s_add_u32 s4, s4, 0x84080
	v_lshl_add_u64 v[6:7], v[242:243], 0, s[84:85]
	s_addc_u32 s5, s5, 0
	global_load_lds_dwordx4 v[6:7], off
	s_add_i32 m0, s24, 0x1c000
	v_lshl_add_u64 v[6:7], s[4:5], 0, v[134:135]
	global_load_lds_dwordx4 v[6:7], off
	s_add_i32 m0, s24, 0x1e000
	v_lshl_add_u64 v[6:7], s[4:5], 0, v[158:159]
	global_load_lds_dwordx4 v[6:7], off
	s_mov_b32 m0, s29
	v_lshl_add_u64 v[6:7], v[244:245], 0, s[84:85]
	global_load_lds_dwordx4 v[6:7], off
	s_mov_b32 m0, s30
	v_lshl_add_u64 v[6:7], v[246:247], 0, s[84:85]
	global_load_lds_dwordx4 v[6:7], off
	s_waitcnt vmcnt(8)
	s_waitcnt lgkmcnt(0)
	s_setprio 1
	s_barrier
	v_mfma_f32_16x16x32_bf16 v[64:67], v[174:177], v[208:211], v[64:67]
	v_mfma_f32_16x16x32_bf16 v[60:63], v[184:187], v[208:211], v[60:63]
	v_mfma_f32_16x16x32_bf16 v[48:51], v[174:177], v[216:219], v[48:51]
	v_mfma_f32_16x16x32_bf16 v[44:47], v[184:187], v[216:219], v[44:47]
	v_mfma_f32_16x16x32_bf16 v[32:35], v[174:177], v[224:227], v[32:35]
	v_mfma_f32_16x16x32_bf16 v[28:31], v[184:187], v[224:227], v[28:31]
	v_mfma_f32_16x16x32_bf16 v[16:19], v[174:177], v[232:235], v[16:19]
	v_mfma_f32_16x16x32_bf16 v[12:15], v[184:187], v[232:235], v[12:15]
	v_mfma_f32_16x16x32_bf16 v[64:67], v[178:181], v[212:215], v[64:67]
	v_mfma_f32_16x16x32_bf16 v[60:63], v[188:191], v[212:215], v[60:63]
	v_mfma_f32_16x16x32_bf16 v[48:51], v[178:181], v[220:223], v[48:51]
	v_mfma_f32_16x16x32_bf16 v[44:47], v[188:191], v[220:223], v[44:47]
	v_mfma_f32_16x16x32_bf16 v[32:35], v[178:181], v[228:231], v[32:35]
	v_mfma_f32_16x16x32_bf16 v[28:31], v[188:191], v[228:231], v[28:31]
	v_mfma_f32_16x16x32_bf16 v[16:19], v[178:181], v[236:239], v[16:19]
	v_mfma_f32_16x16x32_bf16 v[12:15], v[188:191], v[236:239], v[12:15]
	v_mfma_f32_16x16x32_bf16 v[56:59], v[192:195], v[208:211], v[56:59]
	v_mfma_f32_16x16x32_bf16 v[52:55], v[200:203], v[208:211], v[52:55]
	v_mfma_f32_16x16x32_bf16 v[40:43], v[192:195], v[216:219], v[40:43]
	v_mfma_f32_16x16x32_bf16 v[36:39], v[200:203], v[216:219], v[36:39]
	v_mfma_f32_16x16x32_bf16 v[24:27], v[192:195], v[224:227], v[24:27]
	v_mfma_f32_16x16x32_bf16 v[20:23], v[200:203], v[224:227], v[20:23]
	v_mfma_f32_16x16x32_bf16 v[6:9], v[192:195], v[232:235], v[8:11]
	v_mfma_f32_16x16x32_bf16 v[2:5], v[200:203], v[232:235], v[2:5]
	v_mfma_f32_16x16x32_bf16 v[56:59], v[196:199], v[212:215], v[56:59]
	v_mfma_f32_16x16x32_bf16 v[52:55], v[204:207], v[212:215], v[52:55]
	v_mfma_f32_16x16x32_bf16 v[40:43], v[196:199], v[220:223], v[40:43]
	v_mfma_f32_16x16x32_bf16 v[36:39], v[204:207], v[220:223], v[36:39]
	v_mfma_f32_16x16x32_bf16 v[24:27], v[196:199], v[228:231], v[24:27]
	v_mfma_f32_16x16x32_bf16 v[20:23], v[204:207], v[228:231], v[20:23]
	v_mfma_f32_16x16x32_bf16 v[8:11], v[196:199], v[236:239], v[6:9]
	v_mfma_f32_16x16x32_bf16 v[4:7], v[204:207], v[236:239], v[2:5]
	s_barrier
	s_setprio 0
	s_add_u32 s18, s18, 0x100
	s_addc_u32 s19, s19, 0
	s_cmp_ge_u32 s42, s41
	s_cbranch_scc0 .LBB0_580
	s_add_u32 s16, s16, 0x200
	s_addc_u32 s17, s17, 0
	s_cmp_lt_u32 s40, 28
	s_cbranch_scc0 .LBB0_583
	s_mov_b32 s40, s41
	s_cmp_eq_u32 s40, 0
	s_cbranch_scc0 .LBB0_578
	s_branch .LBB0_579

; template <class Epi, bool ALIGN_EPI = PG8_ALIGN, bool SP2 = PG8_SP2>
; __device__ __forceinline__ void gemm_phase(LAS uchar* lds, const Gemm g, const StaticOrder& S, const Epi& E) {
;     ...
;         const bool has_next = S.next(ui + 1, nxt);
;         const char* nA = has_next ? (const char*)g.A + (size_t)nxt.pm * tstepA : cA; const char* nB = has_next ? (const char*)g.Bt + (size_t)nxt.pn * tstepB : cB;
.LBB0_664:
	s_andn2_b64 s[0:1], exec, s[4:5]
	s_andn2_b64 vcc, exec, s[4:5]
	s_mov_b64 s[4:5], s[12:13]
	s_cbranch_vccnz .LBB0_666
	v_readlane_b32 s36, v254, 0
	s_mul_i32 s4, s31, 0x88000
	v_readlane_b32 s40, v254, 4
	s_mul_hi_i32 s5, s31, 0x88000
	v_readlane_b32 s41, v254, 5
	s_add_u32 s4, s40, s4
	s_addc_u32 s5, s41, s5
	v_readlane_b32 s37, v254, 1
	v_readlane_b32 s38, v254, 2
	v_readlane_b32 s39, v254, 3
	v_readlane_b32 s42, v254, 6
	v_readlane_b32 s43, v254, 7

; template <class Epi, bool ALIGN_EPI = PG8_ALIGN, bool SP2 = PG8_SP2>
; __device__ __forceinline__ void gemm_phase(LAS uchar* lds, const Gemm g, const StaticOrder& S, const Epi& E) {
;     ...
;         const bool has_next = S.next(ui + 1, nxt);
;         const char* nA = has_next ? (const char*)g.A + (size_t)nxt.pm * tstepA : cA; const char* nB = has_next ? (const char*)g.Bt + (size_t)nxt.pn * tstepB : cB;
.LBB0_832:
	s_nop 0
	s_andn2_b64 s[0:1], exec, s[4:5]
	s_andn2_b64 vcc, exec, s[4:5]
	s_mov_b64 s[4:5], s[12:13]
	s_cbranch_vccnz .LBB0_834
	s_mul_i32 s4, s31, 0x88000
	v_readlane_b32 s10, v254, 51
	s_mul_hi_i32 s5, s31, 0x88000
	v_readlane_b32 s11, v254, 52
	s_add_u32 s4, s10, s4
	s_addc_u32 s5, s11, s5

; template <class Epi, bool ALIGN_EPI = PG8_ALIGN, bool SP2 = PG8_SP2>
; __device__ __forceinline__ void gemm_phase(LAS uchar* lds, const Gemm g, const StaticOrder& S, const Epi& E) {
;     ...
;         const bool has_next = S.next(ui + 1, nxt);
;         const char* nA = has_next ? (const char*)g.A + (size_t)nxt.pm * tstepA : cA; const char* nB = has_next ? (const char*)g.Bt + (size_t)nxt.pn * tstepB : cB;
.LBB0_1045:
	s_nop 0
	s_andn2_b64 s[4:5], exec, s[0:1]
	s_andn2_b64 vcc, exec, s[0:1]
	s_mov_b64 s[0:1], s[12:13]
	s_cbranch_vccnz .LBB0_1047
	v_readlane_b32 s36, v254, 0
	s_mul_i32 s0, s31, 0x88000
	v_readlane_b32 s40, v254, 4
	s_mul_hi_i32 s1, s31, 0x88000
	v_readlane_b32 s41, v254, 5
	s_add_u32 s0, s40, s0
	s_addc_u32 s1, s41, s1
	v_readlane_b32 s37, v254, 1
	v_readlane_b32 s38, v254, 2
	v_readlane_b32 s39, v254, 3
	v_readlane_b32 s42, v254, 6
	v_readlane_b32 s43, v254, 7

; template <class Epi, bool ALIGN_EPI = PG8_ALIGN, bool SP2 = PG8_SP2>
; __device__ __forceinline__ void gemm_phase(LAS uchar* lds, const Gemm g, const StaticOrder& S, const Epi& E) {
;     ...
;         const bool has_next = S.next(ui + 1, nxt);
;         const char* nA = has_next ? (const char*)g.A + (size_t)nxt.pm * tstepA : cA; const char* nB = has_next ? (const char*)g.Bt + (size_t)nxt.pn * tstepB : cB;
.LBB0_1138:
	s_nop 0
	s_andn2_b64 s[0:1], exec, s[4:5]
	s_andn2_b64 vcc, exec, s[4:5]
	s_mov_b64 s[4:5], s[14:15]
	s_cbranch_vccnz .LBB0_1140
	s_mul_i32 s4, s35, 0x160000
	s_mul_hi_i32 s5, s35, 0x160000
	s_add_u32 s4, s90, s4
	s_addc_u32 s5, s91, s5
